# in-proj prelude: the 16 partial sum-of-squares loads per token issued together (one wait) instead of 15 serialized round trips
# speedup vs baseline: 1.0146x; 1.0020x over previous
.LBB0_90:
	s_or_b64 exec, exec, s[8:9]
	s_and_saveexec_b64 s[4:5], vcc
	s_cbranch_execz .LBB0_87
	v_lshl_or_b32 v6, v4, 8, v2
	v_lshlrev_b32_e32 v6, 2, v6
	s_mov_b64 s[12:13], s[2:3]
	s_nop 0
	global_load_dword v238, v6, s[12:13]
	s_add_u32 s12, s12, 0x10000
	s_addc_u32 s13, s13, 0
	s_nop 0
	global_load_dword v239, v6, s[12:13]
	s_add_u32 s12, s12, 0x10000
	s_addc_u32 s13, s13, 0
	s_nop 0
	global_load_dword v240, v6, s[12:13]
	s_add_u32 s12, s12, 0x10000
	s_addc_u32 s13, s13, 0
	s_nop 0
	global_load_dword v241, v6, s[12:13]
	s_add_u32 s12, s12, 0x10000
	s_addc_u32 s13, s13, 0
	s_nop 0
	global_load_dword v242, v6, s[12:13]
	s_add_u32 s12, s12, 0x10000
	s_addc_u32 s13, s13, 0
	s_nop 0
	global_load_dword v243, v6, s[12:13]
	s_add_u32 s12, s12, 0x10000
	s_addc_u32 s13, s13, 0
	s_nop 0
	global_load_dword v244, v6, s[12:13]
	s_add_u32 s12, s12, 0x10000
	s_addc_u32 s13, s13, 0
	s_nop 0
	global_load_dword v245, v6, s[12:13]
	s_add_u32 s12, s12, 0x10000
	s_addc_u32 s13, s13, 0
	s_nop 0
	global_load_dword v246, v6, s[12:13]
	s_add_u32 s12, s12, 0x10000
	s_addc_u32 s13, s13, 0
	s_nop 0
	global_load_dword v247, v6, s[12:13]
	s_add_u32 s12, s12, 0x10000
	s_addc_u32 s13, s13, 0
	s_nop 0
	global_load_dword v248, v6, s[12:13]
	s_add_u32 s12, s12, 0x10000
	s_addc_u32 s13, s13, 0
	s_nop 0
	global_load_dword v249, v6, s[12:13]
	s_add_u32 s12, s12, 0x10000
	s_addc_u32 s13, s13, 0
	s_nop 0
	global_load_dword v250, v6, s[12:13]
	s_add_u32 s12, s12, 0x10000
	s_addc_u32 s13, s13, 0
	s_nop 0
	global_load_dword v251, v6, s[12:13]
	s_add_u32 s12, s12, 0x10000
	s_addc_u32 s13, s13, 0
	s_nop 0
	global_load_dword v8, v6, s[12:13]
	s_add_u32 s12, s12, 0x10000
	s_addc_u32 s13, s13, 0
	s_nop 0
	global_load_dword v9, v6, s[12:13]
	s_waitcnt vmcnt(0)
	v_add_f32_e32 v5, 0, v238
	v_add_f32_e32 v5, v5, v239
	v_add_f32_e32 v5, v5, v240
	v_add_f32_e32 v5, v5, v241
	v_add_f32_e32 v5, v5, v242
	v_add_f32_e32 v5, v5, v243
	v_add_f32_e32 v5, v5, v244
	v_add_f32_e32 v5, v5, v245
	v_add_f32_e32 v5, v5, v246
	v_add_f32_e32 v5, v5, v247
	v_add_f32_e32 v5, v5, v248
	v_add_f32_e32 v5, v5, v249
	v_add_f32_e32 v5, v5, v250
	v_add_f32_e32 v5, v5, v251
	v_add_f32_e32 v5, v5, v8
	v_add_f32_e32 v5, v5, v9
	v_fmamk_f32 v5, v5, 0x3a800000, v227
	v_rsq_f32_e32 v5, v5
	ds_write_b32 v3, v5
	s_branch .LBB0_87
